# s_setprio 1 during the MFMA phase of the NORM GEMM loops (back to 0 before the LDS-write phase)
# speedup vs baseline: 1.7243x; 1.0026x over previous
.LBB0_104:
	s_waitcnt lgkmcnt(0)
	s_barrier
	s_waitcnt vmcnt(11)
	ds_write_b128 v243, v[160:163] offset:36864
	v_add_u32_e32 v188, s2, v200
	v_add_u32_e32 v188, 0x40, v188
	v_lshl_add_u64 v[160:161], v[188:189], 1, s[24:25]
	global_load_dwordx4 v[160:163], v[160:161], off
	s_waitcnt vmcnt(11)
	ds_write_b128 v243, v[164:167] offset:41472
	v_add_u32_e32 v188, s2, v200
	v_add_u32_e32 v188, 0x8040, v188
	v_lshl_add_u64 v[164:165], v[188:189], 1, s[24:25]
	global_load_dwordx4 v[164:167], v[164:165], off
	s_waitcnt vmcnt(11)
	ds_write_b128 v243, v[168:171] offset:46080
	v_add_u32_e32 v188, s2, v200
	v_add_u32_e32 v188, 0x10040, v188
	v_lshl_add_u64 v[168:169], v[188:189], 1, s[24:25]
	global_load_dwordx4 v[168:171], v[168:169], off
	s_waitcnt vmcnt(11)
	ds_write_b128 v243, v[172:175] offset:50688
	v_add_u32_e32 v188, s2, v200
	v_add_u32_e32 v188, 0x18040, v188
	v_lshl_add_u64 v[172:173], v[188:189], 1, s[24:25]
	global_load_dwordx4 v[172:175], v[172:173], off
	s_waitcnt vmcnt(11)
	ds_write_b128 v243, v[156:159]
	v_dot2c_f32_bf16_e32 v197, v156, v156
	v_dot2c_f32_bf16_e32 v197, v157, v157
	v_dot2c_f32_bf16_e32 v197, v158, v158
	v_dot2c_f32_bf16_e32 v197, v159, v159
	v_add_u32_e32 v188, s2, v198
	v_add_u32_e32 v188, 0x40, v188
	v_lshl_add_u64 v[156:157], v[188:189], 1, s[36:37]
	global_load_dwordx4 v[156:159], v[156:157], off
	s_waitcnt vmcnt(11)
	ds_write_b128 v243, v[152:155] offset:4608
	v_dot2c_f32_bf16_e32 v196, v152, v152
	v_dot2c_f32_bf16_e32 v196, v153, v153
	v_dot2c_f32_bf16_e32 v196, v154, v154
	v_dot2c_f32_bf16_e32 v196, v155, v155
	v_add_u32_e32 v188, s2, v198
	v_add_u32_e32 v188, 0x8040, v188
	v_lshl_add_u64 v[152:153], v[188:189], 1, s[36:37]
	global_load_dwordx4 v[152:155], v[152:153], off
	s_waitcnt vmcnt(11)
	ds_write_b128 v243, v[148:151] offset:9216
	v_dot2c_f32_bf16_e32 v195, v148, v148
	v_dot2c_f32_bf16_e32 v195, v149, v149
	v_dot2c_f32_bf16_e32 v195, v150, v150
	v_dot2c_f32_bf16_e32 v195, v151, v151
	v_add_u32_e32 v188, s2, v198
	v_add_u32_e32 v188, 0x10040, v188
	v_lshl_add_u64 v[148:149], v[188:189], 1, s[36:37]
	global_load_dwordx4 v[148:151], v[148:149], off
	s_waitcnt vmcnt(11)
	ds_write_b128 v243, v[144:147] offset:13824
	v_dot2c_f32_bf16_e32 v194, v144, v144
	v_dot2c_f32_bf16_e32 v194, v145, v145
	v_dot2c_f32_bf16_e32 v194, v146, v146
	v_dot2c_f32_bf16_e32 v194, v147, v147
	v_add_u32_e32 v188, s2, v198
	v_add_u32_e32 v188, 0x18040, v188
	v_lshl_add_u64 v[144:145], v[188:189], 1, s[36:37]
	global_load_dwordx4 v[144:147], v[144:145], off
	s_waitcnt vmcnt(11)
	ds_write_b128 v243, v[140:143] offset:18432
	v_dot2c_f32_bf16_e32 v193, v140, v140
	v_dot2c_f32_bf16_e32 v193, v141, v141
	v_dot2c_f32_bf16_e32 v193, v142, v142
	v_dot2c_f32_bf16_e32 v193, v143, v143
	v_add_u32_e32 v188, s2, v198
	v_add_u32_e32 v188, 0x20040, v188
	v_lshl_add_u64 v[140:141], v[188:189], 1, s[36:37]
	global_load_dwordx4 v[140:143], v[140:141], off
	s_waitcnt vmcnt(11)
	ds_write_b128 v243, v[136:139] offset:23040
	v_dot2c_f32_bf16_e32 v192, v136, v136
	v_dot2c_f32_bf16_e32 v192, v137, v137
	v_dot2c_f32_bf16_e32 v192, v138, v138
	v_dot2c_f32_bf16_e32 v192, v139, v139
	v_add_u32_e32 v188, s2, v198
	v_add_u32_e32 v188, 0x28040, v188
	v_lshl_add_u64 v[136:137], v[188:189], 1, s[36:37]
	global_load_dwordx4 v[136:139], v[136:137], off
	s_waitcnt vmcnt(11)
	ds_write_b128 v243, v[132:135] offset:27648
	v_dot2c_f32_bf16_e32 v191, v132, v132
	v_dot2c_f32_bf16_e32 v191, v133, v133
	v_dot2c_f32_bf16_e32 v191, v134, v134
	v_dot2c_f32_bf16_e32 v191, v135, v135
	v_add_u32_e32 v188, s2, v198
	v_add_u32_e32 v188, 0x30040, v188
	v_lshl_add_u64 v[132:133], v[188:189], 1, s[36:37]
	global_load_dwordx4 v[132:135], v[132:133], off
	s_waitcnt vmcnt(11)
	ds_write_b128 v243, v[128:131] offset:32256
	v_dot2c_f32_bf16_e32 v190, v128, v128
	v_dot2c_f32_bf16_e32 v190, v129, v129
	v_dot2c_f32_bf16_e32 v190, v130, v130
	v_dot2c_f32_bf16_e32 v190, v131, v131
	v_add_u32_e32 v188, s2, v198
	v_add_u32_e32 v188, 0x38040, v188
	v_lshl_add_u64 v[128:129], v[188:189], 1, s[36:37]
	global_load_dwordx4 v[128:131], v[128:129], off
	s_waitcnt lgkmcnt(0)
	s_barrier
	s_setprio 1
	ds_read_b128 v[244:247], v242 offset:36864
	ds_read_b128 v[184:187], v242 offset:41472
	ds_read_b128 v[248:251], v201
	ds_read_b128 v[232:235], v201 offset:4608
	s_waitcnt lgkmcnt(1)
	v_mfma_f32_32x32x16_bf16 v[112:127], v[248:251], v[244:247], v[112:127]
	v_mfma_f32_32x32x16_bf16 v[96:111], v[248:251], v[184:187], v[96:111]
	ds_read_b128 v[248:251], v201 offset:9216
	s_waitcnt lgkmcnt(1)
	v_mfma_f32_32x32x16_bf16 v[80:95], v[232:235], v[244:247], v[80:95]
	v_mfma_f32_32x32x16_bf16 v[64:79], v[232:235], v[184:187], v[64:79]
	ds_read_b128 v[232:235], v199
	ds_read_b128 v[176:179], v242 offset:36896
	ds_read_b128 v[180:183], v242 offset:41504
	s_waitcnt lgkmcnt(3)
	v_mfma_f32_32x32x16_bf16 v[48:63], v[248:251], v[244:247], v[48:63]
	v_mfma_f32_32x32x16_bf16 v[32:47], v[248:251], v[184:187], v[32:47]
	ds_read_b128 v[248:251], v201 offset:32
	s_waitcnt lgkmcnt(3)
	v_mfma_f32_32x32x16_bf16 v[16:31], v[232:235], v[244:247], v[16:31]
	v_mfma_f32_32x32x16_bf16 v[0:15], v[232:235], v[184:187], v[0:15]
	ds_read_b128 v[232:235], v201 offset:4640
	s_waitcnt lgkmcnt(1)
	v_mfma_f32_32x32x16_bf16 v[112:127], v[248:251], v[176:179], v[112:127]
	v_mfma_f32_32x32x16_bf16 v[96:111], v[248:251], v[180:183], v[96:111]
	ds_read_b128 v[248:251], v201 offset:9248
	s_waitcnt lgkmcnt(1)
	v_mfma_f32_32x32x16_bf16 v[80:95], v[232:235], v[176:179], v[80:95]
	v_mfma_f32_32x32x16_bf16 v[64:79], v[232:235], v[180:183], v[64:79]
	ds_read_b128 v[232:235], v199 offset:32
	ds_read_b128 v[244:247], v242 offset:36928
	ds_read_b128 v[184:187], v242 offset:41536
	s_waitcnt lgkmcnt(3)
; template <bool NORM, bool DEEP, int MTW, int KSEG, class HOOK>
; DI void gemm_core_h(const bfu* __restrict__ A, int lda, const bfu* __restrict__ Bt, int ldb, int K, int m0, int n0,
;                     f32x16 (&acc)[MTW][2], char* smem, HOOK hook) {
;     ...
;   if (DEEP) {
;     for (int kt = 0; kt < nk; kt += 2) {
;       GEMM_STEP(ra0, rb0, kt, 2)
;       GEMM_STEP(ra1, rb1, kt + 1, 2)
;     }
;   } else {
;     for (int kt = 0; kt < nk; ++kt) {
;       GEMM_STEP(ra0, rb0, kt, 1)
	v_mfma_f32_32x32x16_bf16 v[48:63], v[248:251], v[176:179], v[48:63]
	v_mfma_f32_32x32x16_bf16 v[32:47], v[248:251], v[180:183], v[32:47]
	ds_read_b128 v[248:251], v201 offset:64
	s_waitcnt lgkmcnt(3)
	v_mfma_f32_32x32x16_bf16 v[16:31], v[232:235], v[176:179], v[16:31]
	v_mfma_f32_32x32x16_bf16 v[0:15], v[232:235], v[180:183], v[0:15]
	ds_read_b128 v[232:235], v201 offset:4672
	s_waitcnt lgkmcnt(1)
	v_mfma_f32_32x32x16_bf16 v[112:127], v[248:251], v[244:247], v[112:127]
	v_mfma_f32_32x32x16_bf16 v[96:111], v[248:251], v[184:187], v[96:111]
	ds_read_b128 v[248:251], v201 offset:9280
	s_waitcnt lgkmcnt(1)
	v_mfma_f32_32x32x16_bf16 v[80:95], v[232:235], v[244:247], v[80:95]
	v_mfma_f32_32x32x16_bf16 v[64:79], v[232:235], v[184:187], v[64:79]
	ds_read_b128 v[232:235], v199 offset:64
	ds_read_b128 v[176:179], v242 offset:36960
	ds_read_b128 v[180:183], v242 offset:41568
	s_waitcnt lgkmcnt(3)
	v_mfma_f32_32x32x16_bf16 v[48:63], v[248:251], v[244:247], v[48:63]
	v_mfma_f32_32x32x16_bf16 v[32:47], v[248:251], v[184:187], v[32:47]
	ds_read_b128 v[248:251], v201 offset:96
	s_waitcnt lgkmcnt(3)
	v_mfma_f32_32x32x16_bf16 v[16:31], v[232:235], v[244:247], v[16:31]
	v_mfma_f32_32x32x16_bf16 v[0:15], v[232:235], v[184:187], v[0:15]
	ds_read_b128 v[232:235], v201 offset:4704
	s_waitcnt lgkmcnt(1)
	v_mfma_f32_32x32x16_bf16 v[112:127], v[248:251], v[176:179], v[112:127]
	v_mfma_f32_32x32x16_bf16 v[96:111], v[248:251], v[180:183], v[96:111]
	ds_read_b128 v[248:251], v201 offset:9312
	s_waitcnt lgkmcnt(1)
	v_mfma_f32_32x32x16_bf16 v[80:95], v[232:235], v[176:179], v[80:95]
	v_mfma_f32_32x32x16_bf16 v[64:79], v[232:235], v[180:183], v[64:79]
	ds_read_b128 v[232:235], v199 offset:96
	s_waitcnt lgkmcnt(1)
	v_mfma_f32_32x32x16_bf16 v[48:63], v[248:251], v[176:179], v[48:63]
	v_mfma_f32_32x32x16_bf16 v[32:47], v[248:251], v[180:183], v[32:47]
	s_waitcnt lgkmcnt(0)
	v_mfma_f32_32x32x16_bf16 v[16:31], v[232:235], v[176:179], v[16:31]
	v_mfma_f32_32x32x16_bf16 v[0:15], v[232:235], v[180:183], v[0:15]
	s_setprio 0
	s_add_i32 s2, s2, 64
	s_cmpk_eq_i32 s2, 0x3c0
	s_cbranch_scc0 .LBB0_104
	s_waitcnt vmcnt(0)
	s_waitcnt lgkmcnt(0)
	s_barrier
	s_waitcnt vmcnt(11)
	ds_write_b128 v243, v[156:159]
	s_waitcnt vmcnt(10)
	ds_write_b128 v243, v[152:155] offset:4608
	s_waitcnt vmcnt(9)
	ds_write_b128 v243, v[148:151] offset:9216
	s_waitcnt vmcnt(8)
	ds_write_b128 v243, v[144:147] offset:13824
	s_waitcnt vmcnt(7)
	ds_write_b128 v243, v[140:143] offset:18432
	s_waitcnt vmcnt(6)
	ds_write_b128 v243, v[136:139] offset:23040
	s_waitcnt vmcnt(5)
	ds_write_b128 v243, v[132:135] offset:27648
	s_waitcnt vmcnt(4)
	ds_write_b128 v243, v[128:131] offset:32256
	s_waitcnt vmcnt(3)
	ds_write_b128 v243, v[160:163] offset:36864
	s_waitcnt vmcnt(2)
	ds_write_b128 v243, v[164:167] offset:41472
	s_waitcnt vmcnt(1)
	ds_write_b128 v243, v[168:171] offset:46080
	s_waitcnt vmcnt(0)
	ds_write_b128 v243, v[172:175] offset:50688
	s_waitcnt lgkmcnt(0)
	s_barrier
; template <bool NORM, bool DEEP, int MTW, int KSEG, class HOOK>
; DI void gemm_core_h(const bfu* __restrict__ A, int lda, const bfu* __restrict__ Bt, int ldb, int K, int m0, int n0,
;                     f32x16 (&acc)[MTW][2], char* smem, HOOK hook) {
;     ...
;   if (NORM) {
; #pragma unroll
;     for (int j = 0; j < NA; ++j) {
;       float v = ssq[j];
;       v += __shfl_xor(v, 1); v += __shfl_xor(v, 2); v += __shfl_xor(v, 4);
;       if (lkc == 0) rstd_s[lrow + 32 * j] = rsqrtf(v / (float)K + EPS);
;     }
	ds_read_b128 v[160:163], v201
	ds_read_b128 v[164:167], v242 offset:36864
	ds_read_b128 v[168:171], v242 offset:41472
	s_waitcnt lgkmcnt(1)
	v_mfma_f32_32x32x16_bf16 v[112:127], v[160:163], v[164:167], v[112:127]
	v_lshlrev_b32_e32 v176, 16, v156
	v_and_b32_e32 v156, 0xffff0000, v156
	v_mul_f32_e32 v156, v156, v156
	v_fmac_f32_e32 v156, v176, v176
	v_add_f32_e32 v156, v197, v156
	s_waitcnt lgkmcnt(0)
	v_mfma_f32_32x32x16_bf16 v[96:111], v[160:163], v[168:171], v[96:111]
	ds_read_b128 v[160:163], v201 offset:4608
	s_waitcnt lgkmcnt(0)
	v_mfma_f32_32x32x16_bf16 v[80:95], v[160:163], v[164:167], v[80:95]
	v_mfma_f32_32x32x16_bf16 v[64:79], v[160:163], v[168:171], v[64:79]
	ds_read_b128 v[160:163], v201 offset:9216
	s_waitcnt lgkmcnt(0)
	v_mfma_f32_32x32x16_bf16 v[48:63], v[160:163], v[164:167], v[48:63]
	v_mfma_f32_32x32x16_bf16 v[32:47], v[160:163], v[168:171], v[32:47]
	ds_read_b128 v[160:163], v199
	s_waitcnt lgkmcnt(0)
	v_mfma_f32_32x32x16_bf16 v[16:31], v[160:163], v[164:167], v[16:31]
	v_mfma_f32_32x32x16_bf16 v[0:15], v[160:163], v[168:171], v[0:15]
	ds_read_b128 v[160:163], v201 offset:32
	ds_read_b128 v[164:167], v242 offset:36896
	ds_read_b128 v[168:171], v242 offset:41504
	s_waitcnt lgkmcnt(1)
	v_mfma_f32_32x32x16_bf16 v[112:127], v[160:163], v[164:167], v[112:127]
	s_waitcnt lgkmcnt(0)
	v_mfma_f32_32x32x16_bf16 v[96:111], v[160:163], v[168:171], v[96:111]
	ds_read_b128 v[160:163], v201 offset:4640
	s_waitcnt lgkmcnt(0)
	v_mfma_f32_32x32x16_bf16 v[80:95], v[160:163], v[164:167], v[80:95]
	v_mfma_f32_32x32x16_bf16 v[64:79], v[160:163], v[168:171], v[64:79]
	ds_read_b128 v[160:163], v201 offset:9248
	s_waitcnt lgkmcnt(0)
	v_mfma_f32_32x32x16_bf16 v[48:63], v[160:163], v[164:167], v[48:63]
	v_mfma_f32_32x32x16_bf16 v[32:47], v[160:163], v[168:171], v[32:47]
	ds_read_b128 v[160:163], v199 offset:32
	s_waitcnt lgkmcnt(0)
	v_mfma_f32_32x32x16_bf16 v[16:31], v[160:163], v[164:167], v[16:31]
	v_mfma_f32_32x32x16_bf16 v[0:15], v[160:163], v[168:171], v[0:15]
	ds_read_b128 v[160:163], v201 offset:64
	ds_read_b128 v[164:167], v242 offset:36928
	ds_read_b128 v[168:171], v242 offset:41536
	s_waitcnt lgkmcnt(1)
	v_mfma_f32_32x32x16_bf16 v[112:127], v[160:163], v[164:167], v[112:127]
	s_waitcnt lgkmcnt(0)
	v_mfma_f32_32x32x16_bf16 v[96:111], v[160:163], v[168:171], v[96:111]
	ds_read_b128 v[160:163], v201 offset:4672
	s_waitcnt lgkmcnt(0)
	v_mfma_f32_32x32x16_bf16 v[80:95], v[160:163], v[164:167], v[80:95]
	v_mfma_f32_32x32x16_bf16 v[64:79], v[160:163], v[168:171], v[64:79]
	ds_read_b128 v[160:163], v201 offset:9280
	s_waitcnt lgkmcnt(0)
	v_mfma_f32_32x32x16_bf16 v[48:63], v[160:163], v[164:167], v[48:63]
	v_mfma_f32_32x32x16_bf16 v[32:47], v[160:163], v[168:171], v[32:47]
	ds_read_b128 v[160:163], v199 offset:64
	s_waitcnt lgkmcnt(0)
	v_mfma_f32_32x32x16_bf16 v[16:31], v[160:163], v[164:167], v[16:31]
	v_mfma_f32_32x32x16_bf16 v[0:15], v[160:163], v[168:171], v[0:15]
	ds_read_b128 v[164:167], v201 offset:96
	ds_read_b128 v[168:171], v242 offset:36960
	ds_read_b128 v[160:163], v242 offset:41568
	ds_read_b128 v[172:175], v201 offset:4704
	s_waitcnt lgkmcnt(2)
	v_mfma_f32_32x32x16_bf16 v[112:127], v[164:167], v[168:171], v[112:127]
	s_waitcnt lgkmcnt(1)
	v_mfma_f32_32x32x16_bf16 v[96:111], v[164:167], v[160:163], v[96:111]
	v_lshlrev_b32_e32 v164, 16, v157
	v_and_b32_e32 v157, 0xffff0000, v157
	v_mul_f32_e32 v157, v157, v157
	v_fmac_f32_e32 v157, v164, v164
	v_add_f32_e32 v156, v157, v156
	v_lshlrev_b32_e32 v157, 16, v158
	v_and_b32_e32 v158, 0xffff0000, v158
	v_mul_f32_e32 v158, v158, v158
	ds_read_b128 v[164:167], v201 offset:9312
	v_fmac_f32_e32 v158, v157, v157
	v_add_f32_e32 v156, v158, v156
	v_and_b32_e32 v158, 0xffff0000, v159
	v_lshlrev_b32_e32 v157, 16, v159
	v_mul_f32_e32 v158, v158, v158
	v_mbcnt_hi_u32_b32 v159, -1, v226
	v_fmac_f32_e32 v158, v157, v157
	v_and_b32_e32 v157, 64, v159
	v_add_f32_e32 v158, v158, v156
	v_xor_b32_e32 v156, 1, v159
	v_add_u32_e32 v176, 64, v157
	v_cmp_lt_i32_e64 s[2:3], v156, v176
	s_waitcnt lgkmcnt(1)
	v_mfma_f32_32x32x16_bf16 v[80:95], v[172:175], v[168:171], v[80:95]
	v_xor_b32_e32 v157, 2, v159
	v_cndmask_b32_e64 v156, v159, v156, s[2:3]
	v_lshlrev_b32_e32 v156, 2, v156
	v_cmp_lt_i32_e64 s[2:3], v157, v176
	s_nop 1
	v_cndmask_b32_e64 v157, v159, v157, s[2:3]
	v_mfma_f32_32x32x16_bf16 v[64:79], v[172:175], v[160:163], v[64:79]
	ds_read_b128 v[172:175], v199 offset:96
	v_lshlrev_b32_e32 v157, 2, v157
	s_waitcnt lgkmcnt(1)
	v_mfma_f32_32x32x16_bf16 v[48:63], v[164:167], v[168:171], v[48:63]
	v_mfma_f32_32x32x16_bf16 v[32:47], v[164:167], v[160:163], v[32:47]
	ds_bpermute_b32 v164, v156, v158
	v_xor_b32_e32 v165, 4, v159
	v_cmp_lt_i32_e64 s[2:3], v165, v176
	s_waitcnt lgkmcnt(0)
	v_add_f32_e32 v164, v158, v164
	ds_bpermute_b32 v166, v157, v164
	v_mfma_f32_32x32x16_bf16 v[16:31], v[172:175], v[168:171], v[16:31]
	v_cndmask_b32_e64 v158, v159, v165, s[2:3]
	v_lshlrev_b32_e32 v159, 2, v158
	v_cmp_eq_u32_e64 s[2:3], 0, v241
	s_waitcnt lgkmcnt(0)
	v_add_f32_e32 v164, v164, v166
	ds_bpermute_b32 v165, v159, v164
	v_lshlrev_b32_e32 v158, 2, v240
	v_mfma_f32_32x32x16_bf16 v[0:15], v[172:175], v[160:163], v[0:15]
	s_and_saveexec_b64 s[8:9], s[2:3]
	s_cbranch_execz .LBB0_107
	s_waitcnt lgkmcnt(0)
	v_add_f32_e32 v160, v164, v165
	v_fmamk_f32 v160, v160, 0x3a800000, v225
	s_mov_b32 s4, 0x800000
	v_mul_f32_e32 v161, 0x4b800000, v160
	v_cmp_gt_f32_e64 s[4:5], s4, v160
	s_nop 1
	v_cndmask_b32_e64 v160, v160, v161, s[4:5]
	v_rsq_f32_e32 v160, v160
	s_nop 0
	v_mul_f32_e32 v161, 0x45800000, v160
	v_cndmask_b32_e64 v160, v160, v161, s[4:5]
	ds_write_b32 v158, v160 offset:55296

.LBB0_782:
	s_waitcnt lgkmcnt(0)
	s_barrier
	v_readlane_b32 s52, v253, 32
	v_readlane_b32 s66, v253, 46
	v_readlane_b32 s67, v253, 47
	v_readlane_b32 s53, v253, 33
	v_readlane_b32 s54, v253, 34
	v_readlane_b32 s55, v253, 35
	v_readlane_b32 s56, v253, 36
	v_readlane_b32 s57, v253, 37
	v_readlane_b32 s58, v253, 38
	v_readlane_b32 s59, v253, 39
	v_readlane_b32 s60, v253, 40
	v_readlane_b32 s61, v253, 41
	v_readlane_b32 s62, v253, 42
	v_readlane_b32 s63, v253, 43
	v_readlane_b32 s64, v253, 44
	v_readlane_b32 s65, v253, 45
	s_waitcnt vmcnt(11)
	ds_write_b128 v212, v[160:163] offset:36864
	v_add_u32_e32 v188, s2, v204
	v_add_u32_e32 v188, 0x40, v188
	v_lshl_add_u64 v[160:161], v[188:189], 1, s[66:67]
	global_load_dwordx4 v[160:163], v[160:161], off
	s_waitcnt vmcnt(11)
	ds_write_b128 v212, v[164:167] offset:41472
	v_add_u32_e32 v188, s2, v204
	v_add_u32_e32 v188, 0x8040, v188
	v_lshl_add_u64 v[164:165], v[188:189], 1, s[66:67]
	global_load_dwordx4 v[164:167], v[164:165], off
	s_waitcnt vmcnt(11)
	ds_write_b128 v212, v[168:171] offset:46080
	v_add_u32_e32 v188, s2, v204
	v_add_u32_e32 v188, 0x10040, v188
	v_lshl_add_u64 v[168:169], v[188:189], 1, s[66:67]
	global_load_dwordx4 v[168:171], v[168:169], off
	s_waitcnt vmcnt(11)
	ds_write_b128 v212, v[172:175] offset:50688
	v_add_u32_e32 v188, s2, v204
	v_add_u32_e32 v188, 0x18040, v188
	v_lshl_add_u64 v[172:173], v[188:189], 1, s[66:67]
	global_load_dwordx4 v[172:175], v[172:173], off
	s_waitcnt vmcnt(11)
	ds_write_b128 v212, v[156:159]
	v_dot2c_f32_bf16_e32 v201, v156, v156
	v_dot2c_f32_bf16_e32 v201, v157, v157
	v_dot2c_f32_bf16_e32 v201, v158, v158
	v_dot2c_f32_bf16_e32 v201, v159, v159
	v_add_u32_e32 v188, s2, v202
	v_add_u32_e32 v188, 0x40, v188
	v_lshl_add_u64 v[156:157], v[188:189], 1, s[38:39]
	global_load_dwordx4 v[156:159], v[156:157], off
	s_waitcnt vmcnt(11)
	ds_write_b128 v212, v[152:155] offset:4608
	v_dot2c_f32_bf16_e32 v200, v152, v152
	v_dot2c_f32_bf16_e32 v200, v153, v153
	v_dot2c_f32_bf16_e32 v200, v154, v154
	v_dot2c_f32_bf16_e32 v200, v155, v155
	v_add_u32_e32 v188, s2, v202
	v_add_u32_e32 v188, 0x8040, v188
	v_lshl_add_u64 v[152:153], v[188:189], 1, s[38:39]
	global_load_dwordx4 v[152:155], v[152:153], off
	s_waitcnt vmcnt(11)
	ds_write_b128 v212, v[148:151] offset:9216
	v_dot2c_f32_bf16_e32 v199, v148, v148
	v_dot2c_f32_bf16_e32 v199, v149, v149
	v_dot2c_f32_bf16_e32 v199, v150, v150
	v_dot2c_f32_bf16_e32 v199, v151, v151
	v_add_u32_e32 v188, s2, v202
	v_add_u32_e32 v188, 0x10040, v188
	v_lshl_add_u64 v[148:149], v[188:189], 1, s[38:39]
	global_load_dwordx4 v[148:151], v[148:149], off
	s_waitcnt vmcnt(11)
	ds_write_b128 v212, v[144:147] offset:13824
	v_dot2c_f32_bf16_e32 v198, v144, v144
	v_dot2c_f32_bf16_e32 v198, v145, v145
	v_dot2c_f32_bf16_e32 v198, v146, v146
	v_dot2c_f32_bf16_e32 v198, v147, v147
	v_add_u32_e32 v188, s2, v202
	v_add_u32_e32 v188, 0x18040, v188
	v_lshl_add_u64 v[144:145], v[188:189], 1, s[38:39]
	global_load_dwordx4 v[144:147], v[144:145], off
	s_waitcnt vmcnt(11)
	ds_write_b128 v212, v[140:143] offset:18432
	v_dot2c_f32_bf16_e32 v197, v140, v140
	v_dot2c_f32_bf16_e32 v197, v141, v141
	v_dot2c_f32_bf16_e32 v197, v142, v142
	v_dot2c_f32_bf16_e32 v197, v143, v143
	v_add_u32_e32 v188, s2, v202
	v_add_u32_e32 v188, 0x20040, v188
	v_lshl_add_u64 v[140:141], v[188:189], 1, s[38:39]
	global_load_dwordx4 v[140:143], v[140:141], off
	s_waitcnt vmcnt(11)
	ds_write_b128 v212, v[136:139] offset:23040
	v_dot2c_f32_bf16_e32 v196, v136, v136
	v_dot2c_f32_bf16_e32 v196, v137, v137
	v_dot2c_f32_bf16_e32 v196, v138, v138
	v_dot2c_f32_bf16_e32 v196, v139, v139
	v_add_u32_e32 v188, s2, v202
	v_add_u32_e32 v188, 0x28040, v188
	v_lshl_add_u64 v[136:137], v[188:189], 1, s[38:39]
	global_load_dwordx4 v[136:139], v[136:137], off
	s_waitcnt vmcnt(11)
	ds_write_b128 v212, v[132:135] offset:27648
	v_dot2c_f32_bf16_e32 v195, v132, v132
	v_dot2c_f32_bf16_e32 v195, v133, v133
	v_dot2c_f32_bf16_e32 v195, v134, v134
	v_dot2c_f32_bf16_e32 v195, v135, v135
	v_add_u32_e32 v188, s2, v202
	v_add_u32_e32 v188, 0x30040, v188
	v_lshl_add_u64 v[132:133], v[188:189], 1, s[38:39]
	global_load_dwordx4 v[132:135], v[132:133], off
	s_waitcnt vmcnt(11)
	ds_write_b128 v212, v[128:131] offset:32256
	v_dot2c_f32_bf16_e32 v194, v128, v128
	v_dot2c_f32_bf16_e32 v194, v129, v129
	v_dot2c_f32_bf16_e32 v194, v130, v130
	v_dot2c_f32_bf16_e32 v194, v131, v131
	v_add_u32_e32 v188, s2, v202
	v_add_u32_e32 v188, 0x38040, v188
	v_lshl_add_u64 v[128:129], v[188:189], 1, s[38:39]
	global_load_dwordx4 v[128:131], v[128:129], off
	s_waitcnt lgkmcnt(0)
	s_barrier
; template <bool NORM, bool DEEP, int MTW, int KSEG, class HOOK>
; DI void gemm_core_h(const bfu* __restrict__ A, int lda, const bfu* __restrict__ Bt, int ldb, int K, int m0, int n0,
;                     f32x16 (&acc)[MTW][2], char* smem, HOOK hook) {
;     ...
;   if (DEEP) {
;     for (int kt = 0; kt < nk; kt += 2) {
;       GEMM_STEP(ra0, rb0, kt, 2)
;       GEMM_STEP(ra1, rb1, kt + 1, 2)
;     }
;   } else {
;     for (int kt = 0; kt < nk; ++kt) {
;       GEMM_STEP(ra0, rb0, kt, 1)
	s_setprio 1
	ds_read_b128 v[214:217], v211 offset:36864
	ds_read_b128 v[184:187], v211 offset:41472
	ds_read_b128 v[218:221], v205
	ds_read_b128 v[238:241], v205 offset:4608
	s_waitcnt lgkmcnt(1)
	v_mfma_f32_32x32x16_bf16 v[112:127], v[218:221], v[214:217], v[112:127]
	v_mfma_f32_32x32x16_bf16 v[96:111], v[218:221], v[184:187], v[96:111]
	ds_read_b128 v[218:221], v205 offset:9216
	s_waitcnt lgkmcnt(1)
	v_mfma_f32_32x32x16_bf16 v[80:95], v[238:241], v[214:217], v[80:95]
	v_mfma_f32_32x32x16_bf16 v[64:79], v[238:241], v[184:187], v[64:79]
	ds_read_b128 v[238:241], v203
	ds_read_b128 v[176:179], v211 offset:36896
	ds_read_b128 v[180:183], v211 offset:41504
	s_waitcnt lgkmcnt(3)
	v_mfma_f32_32x32x16_bf16 v[48:63], v[218:221], v[214:217], v[48:63]
	v_mfma_f32_32x32x16_bf16 v[32:47], v[218:221], v[184:187], v[32:47]
	ds_read_b128 v[218:221], v205 offset:32
	s_waitcnt lgkmcnt(3)
	v_mfma_f32_32x32x16_bf16 v[16:31], v[238:241], v[214:217], v[16:31]
	v_mfma_f32_32x32x16_bf16 v[0:15], v[238:241], v[184:187], v[0:15]
	ds_read_b128 v[238:241], v205 offset:4640
	s_waitcnt lgkmcnt(1)
	v_mfma_f32_32x32x16_bf16 v[112:127], v[218:221], v[176:179], v[112:127]
	v_mfma_f32_32x32x16_bf16 v[96:111], v[218:221], v[180:183], v[96:111]
	ds_read_b128 v[218:221], v205 offset:9248
	s_waitcnt lgkmcnt(1)
	v_mfma_f32_32x32x16_bf16 v[80:95], v[238:241], v[176:179], v[80:95]
	v_mfma_f32_32x32x16_bf16 v[64:79], v[238:241], v[180:183], v[64:79]
	ds_read_b128 v[238:241], v203 offset:32
	ds_read_b128 v[214:217], v211 offset:36928
	ds_read_b128 v[184:187], v211 offset:41536
	s_waitcnt lgkmcnt(3)
	v_mfma_f32_32x32x16_bf16 v[48:63], v[218:221], v[176:179], v[48:63]
	v_mfma_f32_32x32x16_bf16 v[32:47], v[218:221], v[180:183], v[32:47]
	ds_read_b128 v[218:221], v205 offset:64
	s_waitcnt lgkmcnt(3)
	v_mfma_f32_32x32x16_bf16 v[16:31], v[238:241], v[176:179], v[16:31]
	v_mfma_f32_32x32x16_bf16 v[0:15], v[238:241], v[180:183], v[0:15]
	ds_read_b128 v[238:241], v205 offset:4672
	s_waitcnt lgkmcnt(1)
	v_mfma_f32_32x32x16_bf16 v[112:127], v[218:221], v[214:217], v[112:127]
	v_mfma_f32_32x32x16_bf16 v[96:111], v[218:221], v[184:187], v[96:111]
	ds_read_b128 v[218:221], v205 offset:9280
	s_waitcnt lgkmcnt(1)
	v_mfma_f32_32x32x16_bf16 v[80:95], v[238:241], v[214:217], v[80:95]
	v_mfma_f32_32x32x16_bf16 v[64:79], v[238:241], v[184:187], v[64:79]
	ds_read_b128 v[238:241], v203 offset:64
	ds_read_b128 v[176:179], v211 offset:36960
	ds_read_b128 v[180:183], v211 offset:41568
	s_waitcnt lgkmcnt(3)
	v_mfma_f32_32x32x16_bf16 v[48:63], v[218:221], v[214:217], v[48:63]
	v_mfma_f32_32x32x16_bf16 v[32:47], v[218:221], v[184:187], v[32:47]
	ds_read_b128 v[218:221], v205 offset:96
	s_waitcnt lgkmcnt(3)
	v_mfma_f32_32x32x16_bf16 v[16:31], v[238:241], v[214:217], v[16:31]
	v_mfma_f32_32x32x16_bf16 v[0:15], v[238:241], v[184:187], v[0:15]
	ds_read_b128 v[238:241], v205 offset:4704
	s_waitcnt lgkmcnt(1)
	v_mfma_f32_32x32x16_bf16 v[112:127], v[218:221], v[176:179], v[112:127]
	v_mfma_f32_32x32x16_bf16 v[96:111], v[218:221], v[180:183], v[96:111]
	ds_read_b128 v[218:221], v205 offset:9312
	s_waitcnt lgkmcnt(1)
	v_mfma_f32_32x32x16_bf16 v[80:95], v[238:241], v[176:179], v[80:95]
	v_mfma_f32_32x32x16_bf16 v[64:79], v[238:241], v[180:183], v[64:79]
	ds_read_b128 v[238:241], v203 offset:96
	s_waitcnt lgkmcnt(1)
	v_mfma_f32_32x32x16_bf16 v[48:63], v[218:221], v[176:179], v[48:63]
	v_mfma_f32_32x32x16_bf16 v[32:47], v[218:221], v[180:183], v[32:47]
	s_waitcnt lgkmcnt(0)
	v_mfma_f32_32x32x16_bf16 v[16:31], v[238:241], v[176:179], v[16:31]
	v_mfma_f32_32x32x16_bf16 v[0:15], v[238:241], v[180:183], v[0:15]
	s_setprio 0
	s_add_i32 s2, s2, 64
	s_cmpk_eq_i32 s2, 0x3c0
	s_cbranch_scc0 .LBB0_782
	s_waitcnt vmcnt(0)
	s_waitcnt lgkmcnt(0)
	s_barrier
	s_waitcnt vmcnt(11)
	ds_write_b128 v212, v[156:159]
	s_waitcnt vmcnt(10)
	ds_write_b128 v212, v[152:155] offset:4608
	s_waitcnt vmcnt(9)
	ds_write_b128 v212, v[148:151] offset:9216
	s_waitcnt vmcnt(8)
	ds_write_b128 v212, v[144:147] offset:13824
	s_waitcnt vmcnt(7)
	ds_write_b128 v212, v[140:143] offset:18432
	s_waitcnt vmcnt(6)
	ds_write_b128 v212, v[136:139] offset:23040
	s_waitcnt vmcnt(5)
	ds_write_b128 v212, v[132:135] offset:27648
	s_waitcnt vmcnt(4)
	ds_write_b128 v212, v[128:131] offset:32256
	s_waitcnt vmcnt(3)
	ds_write_b128 v212, v[160:163] offset:36864
	s_waitcnt vmcnt(2)
	ds_write_b128 v212, v[164:167] offset:41472
	s_waitcnt vmcnt(1)
	ds_write_b128 v212, v[168:171] offset:46080
	s_waitcnt vmcnt(0)
	ds_write_b128 v212, v[172:175] offset:50688
	s_waitcnt lgkmcnt(0)
	s_barrier
; template <bool NORM, bool DEEP, int MTW, int KSEG, class HOOK>
; DI void gemm_core_h(const bfu* __restrict__ A, int lda, const bfu* __restrict__ Bt, int ldb, int K, int m0, int n0,
;                     f32x16 (&acc)[MTW][2], char* smem, HOOK hook) {
;     ...
;   if (NORM) {
; #pragma unroll
;     for (int j = 0; j < NA; ++j) {
;       float v = ssq[j];
;       v += __shfl_xor(v, 1); v += __shfl_xor(v, 2); v += __shfl_xor(v, 4);
;       if (lkc == 0) rstd_s[lrow + 32 * j] = rsqrtf(v / (float)K + EPS);
;     }
	ds_read_b128 v[160:163], v205
	ds_read_b128 v[164:167], v211 offset:36864
	ds_read_b128 v[168:171], v211 offset:41472
	s_waitcnt lgkmcnt(1)
	v_mfma_f32_32x32x16_bf16 v[112:127], v[160:163], v[164:167], v[112:127]
	s_waitcnt lgkmcnt(0)
	v_mfma_f32_32x32x16_bf16 v[96:111], v[160:163], v[168:171], v[96:111]
	ds_read_b128 v[160:163], v205 offset:4608
	s_waitcnt lgkmcnt(0)
	v_mfma_f32_32x32x16_bf16 v[80:95], v[160:163], v[164:167], v[80:95]
	v_mfma_f32_32x32x16_bf16 v[64:79], v[160:163], v[168:171], v[64:79]
	ds_read_b128 v[160:163], v205 offset:9216
	s_waitcnt lgkmcnt(0)
	v_mfma_f32_32x32x16_bf16 v[48:63], v[160:163], v[164:167], v[48:63]
	v_mfma_f32_32x32x16_bf16 v[32:47], v[160:163], v[168:171], v[32:47]
	ds_read_b128 v[160:163], v203
	s_waitcnt lgkmcnt(0)
	v_mfma_f32_32x32x16_bf16 v[16:31], v[160:163], v[164:167], v[16:31]
	v_mfma_f32_32x32x16_bf16 v[0:15], v[160:163], v[168:171], v[0:15]
	ds_read_b128 v[160:163], v205 offset:32
	ds_read_b128 v[164:167], v211 offset:36896
	ds_read_b128 v[168:171], v211 offset:41504
	s_waitcnt lgkmcnt(1)
	v_mfma_f32_32x32x16_bf16 v[112:127], v[160:163], v[164:167], v[112:127]
	s_waitcnt lgkmcnt(0)
	v_mfma_f32_32x32x16_bf16 v[96:111], v[160:163], v[168:171], v[96:111]
	ds_read_b128 v[160:163], v205 offset:4640
	s_waitcnt lgkmcnt(0)
	v_mfma_f32_32x32x16_bf16 v[80:95], v[160:163], v[164:167], v[80:95]
	v_mfma_f32_32x32x16_bf16 v[64:79], v[160:163], v[168:171], v[64:79]
	ds_read_b128 v[160:163], v205 offset:9248
	s_waitcnt lgkmcnt(0)
	v_mfma_f32_32x32x16_bf16 v[48:63], v[160:163], v[164:167], v[48:63]
	v_mfma_f32_32x32x16_bf16 v[32:47], v[160:163], v[168:171], v[32:47]
	ds_read_b128 v[160:163], v203 offset:32
	s_waitcnt lgkmcnt(0)
	v_mfma_f32_32x32x16_bf16 v[16:31], v[160:163], v[164:167], v[16:31]
	v_mfma_f32_32x32x16_bf16 v[0:15], v[160:163], v[168:171], v[0:15]
	ds_read_b128 v[160:163], v205 offset:64
	ds_read_b128 v[164:167], v211 offset:36928
	ds_read_b128 v[168:171], v211 offset:41536
	s_waitcnt lgkmcnt(1)
	v_mfma_f32_32x32x16_bf16 v[112:127], v[160:163], v[164:167], v[112:127]
	s_waitcnt lgkmcnt(0)
	v_mfma_f32_32x32x16_bf16 v[96:111], v[160:163], v[168:171], v[96:111]
	ds_read_b128 v[160:163], v205 offset:4672
	s_waitcnt lgkmcnt(0)
	v_mfma_f32_32x32x16_bf16 v[80:95], v[160:163], v[164:167], v[80:95]
	v_mfma_f32_32x32x16_bf16 v[64:79], v[160:163], v[168:171], v[64:79]
	ds_read_b128 v[160:163], v205 offset:9280
	s_waitcnt lgkmcnt(0)
	v_mfma_f32_32x32x16_bf16 v[48:63], v[160:163], v[164:167], v[48:63]
	v_mfma_f32_32x32x16_bf16 v[32:47], v[160:163], v[168:171], v[32:47]
	ds_read_b128 v[160:163], v203 offset:64
	s_waitcnt lgkmcnt(0)
	v_mfma_f32_32x32x16_bf16 v[16:31], v[160:163], v[164:167], v[16:31]
	v_mfma_f32_32x32x16_bf16 v[0:15], v[160:163], v[168:171], v[0:15]
	ds_read_b128 v[168:171], v205 offset:96
	ds_read_b128 v[164:167], v211 offset:36960
	ds_read_b128 v[160:163], v211 offset:41568
	ds_read_b128 v[172:175], v205 offset:4704
	s_waitcnt lgkmcnt(2)
	v_mfma_f32_32x32x16_bf16 v[112:127], v[168:171], v[164:167], v[112:127]
	s_waitcnt lgkmcnt(1)
	v_mfma_f32_32x32x16_bf16 v[96:111], v[168:171], v[160:163], v[96:111]
	v_lshlrev_b32_e32 v168, 16, v156
	v_and_b32_e32 v156, 0xffff0000, v156
	v_mul_f32_e32 v156, v156, v156
	v_fmac_f32_e32 v156, v168, v168
	v_lshlrev_b32_e32 v168, 16, v157
	v_and_b32_e32 v157, 0xffff0000, v157
	v_mul_f32_e32 v157, v157, v157
	v_add_f32_e32 v156, v201, v156
	v_fmac_f32_e32 v157, v168, v168
	v_add_f32_e32 v156, v157, v156
	v_lshlrev_b32_e32 v157, 16, v158
	v_and_b32_e32 v158, 0xffff0000, v158
	v_mul_f32_e32 v158, v158, v158
	ds_read_b128 v[168:171], v205 offset:9312
	v_fmac_f32_e32 v158, v157, v157
	v_add_f32_e32 v156, v158, v156
	v_and_b32_e32 v158, 0xffff0000, v159
	v_lshlrev_b32_e32 v157, 16, v159
	v_mul_f32_e32 v158, v158, v158
	v_fmac_f32_e32 v158, v157, v157
	v_and_b32_e32 v157, 64, v227
	s_waitcnt lgkmcnt(1)
	v_mfma_f32_32x32x16_bf16 v[80:95], v[172:175], v[164:167], v[80:95]
	v_add_f32_e32 v158, v158, v156
	v_xor_b32_e32 v156, 1, v227
	v_add_u32_e32 v159, 64, v157
	v_cmp_lt_i32_e32 vcc, v156, v159
	v_xor_b32_e32 v157, 2, v227
	s_nop 0
	v_cndmask_b32_e32 v156, v227, v156, vcc
	v_mfma_f32_32x32x16_bf16 v[64:79], v[172:175], v[160:163], v[64:79]
	ds_read_b128 v[172:175], v203 offset:96
	v_lshlrev_b32_e32 v156, 2, v156
	v_cmp_lt_i32_e32 vcc, v157, v159
	s_nop 1
	v_cndmask_b32_e32 v157, v227, v157, vcc
	v_lshlrev_b32_e32 v157, 2, v157
	s_waitcnt lgkmcnt(1)
	v_mfma_f32_32x32x16_bf16 v[48:63], v[168:171], v[164:167], v[48:63]
	v_mfma_f32_32x32x16_bf16 v[32:47], v[168:171], v[160:163], v[32:47]
	ds_bpermute_b32 v168, v156, v158
	v_xor_b32_e32 v169, 4, v227
	v_cmp_lt_i32_e32 vcc, v169, v159
	s_waitcnt lgkmcnt(1)
	v_mfma_f32_32x32x16_bf16 v[16:31], v[172:175], v[164:167], v[16:31]
	s_waitcnt lgkmcnt(0)
	v_add_f32_e32 v164, v158, v168
	ds_bpermute_b32 v165, v157, v164
	v_cndmask_b32_e32 v158, v227, v169, vcc
	v_lshlrev_b32_e32 v159, 2, v158
	v_cmp_eq_u32_e32 vcc, 0, v210
	v_lshlrev_b32_e32 v158, 2, v193
	s_waitcnt lgkmcnt(0)
	v_add_f32_e32 v164, v164, v165
	v_mfma_f32_32x32x16_bf16 v[0:15], v[172:175], v[160:163], v[0:15]
	ds_bpermute_b32 v165, v159, v164
	s_and_saveexec_b64 s[4:5], vcc
	s_cbranch_execz .LBB0_785
	s_waitcnt lgkmcnt(0)
	v_add_f32_e32 v160, v164, v165
	v_fmamk_f32 v160, v160, 0x3a800000, v225
	s_mov_b32 s2, 0x800000
	v_mul_f32_e32 v161, 0x4b800000, v160
	v_cmp_gt_f32_e64 s[2:3], s2, v160
	s_nop 1
	v_cndmask_b32_e64 v160, v160, v161, s[2:3]
	v_rsq_f32_e32 v160, v160
	s_nop 0
	v_mul_f32_e32 v161, 0x45800000, v160
	v_cndmask_b32_e64 v160, v160, v161, s[2:3]
	ds_write_b32 v158, v160 offset:55296
